# NSA_PACK work rebalancing: GEMM-tile blocks (bid<64) skip pack items, their 576 items redistributed to blocks 64..511
# baseline (speedup 1.0000x reference)
.LBB0_582:
	s_andn2_b64 vcc, exec, s[0:1]
	s_cbranch_vccnz .LBB0_709
	s_cmp_lt_i32 s96, 2
	s_mov_b64 s[0:1], -1
	v_readlane_b32 s77, v254, 41
	s_mov_b32 s80, 0x800000
	s_movk_i32 s81, 0x2000
	s_cbranch_scc1 .LBB0_648
	s_cmp_gt_i32 s96, 2
	s_cbranch_scc0 .LBB0_638
	s_cmpk_gt_i32 s63, 0x123f
	s_cbranch_scc1 .LBB0_637
	s_add_u32 s4, s86, 0xdfd5000
	s_addc_u32 s5, s87, 0
	s_add_u32 s44, s86, 0x5ed0000
	s_addc_u32 s45, s87, 0
	s_add_u32 s14, s86, 0x5f50000
	s_addc_u32 s15, s87, 0
	s_lshl_b32 s52, s97, 1
	s_add_u32 s53, s86, 0x1230000
	s_addc_u32 s54, s87, 0
	s_add_u32 s46, s86, 0x15555000
	s_addc_u32 s47, s87, 0
	s_add_u32 s48, s86, 0x155d5000
	v_lshrrev_b32_e32 v0, 3, v215
	s_addc_u32 s49, s87, 0
	v_bfe_u32 v140, v215, 6, 2
	v_and_b32_e32 v0, 4, v0
	s_add_u32 s55, s86, 0xe30000
	v_and_b32_e32 v141, 31, v215
	v_lshl_or_b32 v142, v140, 4, v0
	s_addc_u32 s56, s87, 0
	s_mov_b32 s57, s63
	s_mov_b32 s101, -1
	s_branch .LBB0_588
.LBB0_587:
	s_cmp_lt_u32 s63, 64
	s_cbranch_scc1 .LBB0_637
	s_cmp_lt_i32 s101, 0
	s_cbranch_scc0 .Lmy_np_extra
	s_add_i32 s57, s57, s62
	s_cmpk_gt_i32 s57, 0x123f
	s_cbranch_scc0 .LBB0_588
	s_sub_i32 s101, s63, 64
	s_branch .Lmy_np_chk
.Lmy_np_extra:
	s_addk_i32 s101, 0x1c0
.Lmy_np_chk:
	s_cmpk_ge_i32 s101, 0x240
	s_cbranch_scc1 .LBB0_637
	s_and_b32 s57, s101, 63
	s_lshr_b32 s100, s101, 6
	s_add_i32 s100, s100, 1
	s_lshl_b32 s100, s100, 9
	s_add_i32 s57, s57, s100
